# phase 9 (forget-gate cumsum + skip threshold) merged into phase 10: each workgroup computes its own (b,h) sequence, grid barrier between them replaced by a workgroup barrier; on top of static wave pri
# speedup vs baseline: 1.0029x; 1.0029x over previous
; __device__ __forceinline__ void fox_prep(const Params& P, LAS unsigned char* lds) {
;     ...
;     if (blockIdx.x == 0 && wave == 0) { float mq = 0.f, mk = 0.f;
;         for (int i = lane; i < 128; i += 64) { mq = fmaxf(mq, fabsf(qgn[i])); mk = fmaxf(mk, fabsf(kgn[i])); }
; #pragma unroll
;         for (int o = 1; o < 64; o <<= 1) { mq = fmaxf(mq, __shfl_xor(mq, o)); mk = fmaxf(mk, __shfl_xor(mk, o)); }
;         if (lane == 0) *(float*)(ws + WS_THR) = 2.0f * (128.0f * mq * mk * qs * 1.05f) + 130.0f; }
.LBB0_1246:
	s_or_b64 exec, exec, s[0:1]
	v_mov_b32_e32 v5, v172
	s_cmp_eq_u32 s66, 0
	s_waitcnt lgkmcnt(0)
	s_barrier
	s_mov_b64 s[0:1], -1
	v_cmp_gt_u32_e32 vcc, 64, v5
	v_and_b32_e32 v4, 63, v5
	s_and_b64 s[2:3], s[0:1], vcc
	s_and_saveexec_b64 s[0:1], s[2:3]
	s_cbranch_execz .LBB0_1251
	v_lshlrev_b32_e32 v0, 2, v4
	v_mov_b32_e32 v1, 0
	v_lshl_add_u64 v[2:3], s[90:91], 0, v[0:1]
	s_mov_b64 s[2:3], 0x11900
	v_or_b32_e32 v6, 0xffffffc0, v4
	v_lshl_add_u64 v[2:3], v[2:3], 0, s[2:3]
	s_mov_b64 s[2:3], 0
	s_mov_b64 s[4:5], 0x100
	v_mov_b32_e32 v0, v1

; __device__ __forceinline__ void fox_prep(const Params& P, LAS unsigned char* lds) {
;     ...
;     for (int sq = blockIdx.x; sq < 32; sq += gridDim.x) { const int b = sq >> 4, h = sq & 15; const float bf = ((const float*)(ws + WS_BF))[h];
;         float v[8]; float cum = 0.f;
; #pragma unroll
;         for (int i = 0; i < 8; ++i) v[i] = FLR[(size_t)(b * SEQ + tid * 8 + i) * 16 + h];
; #pragma unroll
;         for (int i = 0; i < 8; ++i) { const float z = v[i] + bf; cum += fminf(z, 0.f) - log1pf(expf(-fabsf(z))); v[i] = cum; }
;         float incl = cum;
; #pragma unroll
;         for (int o = 1; o < 64; o <<= 1) { const float t = __shfl_up(incl, o); if (lane >= o) incl += t; }
.LBB0_1251:
	s_or_b64 exec, exec, s[0:1]
	v_readlane_b32 s5, v237, 0
	s_lshr_b32 s5, s5, 3
	s_cmp_gt_i32 s5, 31
	s_cbranch_scc1 .LBB0_1272
	v_lshlrev_b32_e32 v0, 3, v5
	v_ashrrev_i32_e32 v1, 31, v0
	s_waitcnt lgkmcnt(0)
	v_lshl_add_u64 v[2:3], v[0:1], 2, s[90:91]
	s_mov_b64 s[0:1], 0x300000
	v_add_u32_e32 v1, -1, v175
	v_cmp_eq_u32_e32 vcc, 63, v4
	v_lshl_add_u64 v[2:3], v[2:3], 0, s[0:1]
	v_cmp_gt_u32_e64 s[8:9], 32, v4
	v_cmp_gt_u32_e64 s[10:11], 16, v4
	v_cmp_gt_u32_e64 s[12:13], 8, v4
	v_cmp_gt_u32_e64 s[14:15], 4, v4
	v_cmp_gt_u32_e64 s[16:17], 2, v4
	v_cmp_eq_u32_e64 s[18:19], 0, v4
	v_cmp_lt_i32_e64 s[0:1], v1, v178
	v_add_u32_e32 v4, -2, v175
	v_ashrrev_i32_e32 v6, 6, v5
	v_cndmask_b32_e64 v1, v1, v175, s[0:1]
	v_cmp_lt_i32_e64 s[0:1], v4, v178
	v_lshl_add_u32 v12, v6, 2, 0
	v_lshlrev_b32_e32 v1, 2, v1
	v_cndmask_b32_e64 v4, v4, v175, s[0:1]
	v_lshlrev_b32_e32 v13, 2, v4
	v_add_u32_e32 v4, -4, v175
	v_cmp_lt_i32_e64 s[0:1], v4, v178
	v_cmp_lt_i32_e64 s[20:21], 0, v6
	v_cmp_lt_i32_e64 s[22:23], 1, v6
	v_cndmask_b32_e64 v4, v4, v175, s[0:1]
	v_lshlrev_b32_e32 v14, 2, v4
	v_add_u32_e32 v4, -8, v175
	v_cmp_lt_i32_e64 s[0:1], v4, v178
	v_cmp_lt_i32_e64 s[24:25], 2, v6
	v_cmp_lt_i32_e64 s[26:27], 3, v6
	v_cndmask_b32_e64 v4, v4, v175, s[0:1]
	v_lshlrev_b32_e32 v15, 2, v4
	v_add_u32_e32 v4, -16, v175
	v_cmp_lt_i32_e64 s[0:1], v4, v178
	v_cmp_lt_i32_e64 s[28:29], 4, v6
	v_cmp_lt_i32_e64 s[30:31], 5, v6
	v_cndmask_b32_e64 v4, v4, v175, s[0:1]
	v_lshlrev_b32_e32 v16, 2, v4
	v_subrev_u32_e32 v4, 32, v175
	v_cmp_lt_i32_e64 s[0:1], v4, v178
	v_cmp_lt_i32_e64 s[34:35], 6, v6
	v_cmp_lt_i32_e64 s[36:37], 7, v6
	v_cndmask_b32_e64 v4, v4, v175, s[0:1]
	v_lshlrev_b32_e32 v17, 2, v4
	s_lshl_b32 s3, s5, 8
	s_lshl_b32 s6, s84, 8
	s_mov_b32 s7, 0xbfb8aa3b
	s_mov_b32 s33, 0xb2a5705f
	s_mov_b32 s40, 0x42ce8ed0
	s_mov_b32 s41, 0xc2b17218
	s_mov_b32 s44, 0x7f800000
	v_mov_b32_e32 v18, 0x7f800000
	s_mov_b32 s45, 0x3f2aaaab
	v_mov_b32_e32 v19, 0x3ecc95a3
	s_mov_b32 s46, 0x3f317218
	s_mov_b32 s47, 0x33800000
	s_mov_b32 s2, 0x3fb8aa3b
	v_mov_b32_e32 v20, 0
	s_mov_b32 s4, s5
	s_branch .LBB0_1254

; __device__ __forceinline__ unsigned xb_ld(unsigned* p)              { return __hip_atomic_load(p, __ATOMIC_RELAXED, __HIP_MEMORY_SCOPE_AGENT); }
; __device__ __forceinline__ unsigned xb_add(unsigned* p, unsigned v) { return __hip_atomic_fetch_add(p, v, __ATOMIC_RELAXED, __HIP_MEMORY_SCOPE_AGENT); }
; #define XB_SPIN(cond, bar) do { unsigned _sp = 0; while (cond) { __builtin_amdgcn_s_sleep(1); \
;     if ((++_sp & 255u) == 0u) { if (xb_ld(&(bar)[XB_TMO])) break; if (_sp > XB_SPIN_CAP) { atomicAdd(&(bar)[XB_TMO], 1u); break; } } } } while (0)
; __device__ __forceinline__ void xcd_barrier(const XcdBarrier& b) {
;     asm volatile("s_waitcnt vmcnt(0)" ::: "memory");
;     __syncthreads();
;     if (threadIdx.x == 0) {
;         unsigned* bar = b.bar;
;         __builtin_amdgcn_s_waitcnt(0);
;         unsigned nloc = b.st[0], nx = b.st[1];
;         if (nloc == 0u) { xcd_barrier_complete(bar, b.x, nloc, nx); b.st[0] = nloc; b.st[1] = nx; }
;         const unsigned old = xb_add(&bar[XB_XSUB(b.x)], 1u);
;         const unsigned gen = old / nloc;
;         if (old + 1u == (gen + 1u) * nloc) {
;             __builtin_amdgcn_fence(__ATOMIC_RELEASE, "agent");
;             asm volatile("s_waitcnt vmcnt(0)" ::: "memory");
;             const unsigned og = xb_add(&bar[XB_TOP], 1u);
;             const unsigned tg = og / nx;
;             if (og + 1u != (tg + 1u) * nx) XB_SPIN(xb_ld(&bar[XB_TOP]) < (tg + 1u) * nx, bar);
;             __builtin_amdgcn_fence(__ATOMIC_ACQUIRE, "agent");
;             xb_add(&bar[XB_XGEN(b.x)], 1u);
;             asm volatile("s_waitcnt vmcnt(0)" ::: "memory");
;         } else {
;             XB_SPIN(xb_ld(&bar[XB_XGEN(b.x)]) == gen, bar);
;             __builtin_amdgcn_fence(__ATOMIC_ACQUIRE, "agent");
;             asm volatile("s_waitcnt vmcnt(0)" ::: "memory");
;         }
;     }
;     __syncthreads();
; }
.LBB0_1272:
	s_waitcnt vmcnt(0)
	s_waitcnt lgkmcnt(0)
	s_barrier
	s_mov_b64 s[0:1], exec
